# grid barrier leader: XCD release no longer waits for the acknowledgement of the global generation increment
# speedup vs baseline: 1.0104x; 1.0013x over previous
; __device__ __forceinline__ unsigned xb_ld(unsigned* p)              { return __hip_atomic_load(p, __ATOMIC_RELAXED, __HIP_MEMORY_SCOPE_AGENT); }
; __device__ __forceinline__ unsigned xb_add(unsigned* p, unsigned v) { return __hip_atomic_fetch_add(p, v, __ATOMIC_RELAXED, __HIP_MEMORY_SCOPE_AGENT); }
; #define XB_SPIN(cond, bar) do { unsigned _sp = 0; while (cond) { __builtin_amdgcn_s_sleep(1); \
;     if ((++_sp & 255u) == 0u) { if (xb_ld(&(bar)[XB_TMO])) break; if (_sp > XB_SPIN_CAP) { atomicAdd(&(bar)[XB_TMO], 1u); break; } } } } while (0)
; __device__ __forceinline__ void xcd_barrier(unsigned* bar, volatile LAS unsigned* st, const int tid) {
;     ...
;             const unsigned og = xb_add(&bar[XB_TOP], 1u);
;             const unsigned tg = og / nx;
;             if (og + 1u == (tg + 1u) * nx) xb_add(&bar[XB_TOPGEN], 1u);
;             else XB_SPIN(xb_ld(&bar[XB_TOPGEN]) == tg, bar);
;             __builtin_amdgcn_fence(__ATOMIC_ACQUIRE, "agent");
;             xb_add(&bar[XB_XGEN(x)], 1u);
;             asm volatile("s_waitcnt vmcnt(0)" ::: "memory");
.LBB0_99:
	s_or_b64 exec, exec, s[14:15]
	s_mov_b64 s[14:15], exec
	v_mbcnt_lo_u32_b32 v0, s14, 0
	v_mbcnt_hi_u32_b32 v0, s15, v0
	v_cmp_eq_u32_e32 vcc, 0, v0
	s_waitcnt lgkmcnt(0)
	s_and_saveexec_b64 s[22:23], vcc
	s_cbranch_execz .LBB0_101
	s_bcnt1_i32_b64 s3, s[14:15]
	v_mov_b32_e32 v0, s3
	v_mov_b32_e32 v1, 0x2000
	global_atomic_add v1, v0, s[16:17] offset:1024
